# layer-0 short conv split in two passes: first 24576 rows by all workgroups before attention, remaining rows deferred to the 136 workgroups without a 16-row attention unit
# baseline (speedup 1.0000x reference)
; __device__ __forceinline__ void conv_pass(const bf16* GB, const bf16* U, const float* cw  , bf16* AO, int gw, int NGW, int lane) {
;     const int c0 = lane * 8;
;     f32x4 w[3][2];
; #pragma unroll
;     for (int k = 0; k < 3; ++k) { w[k][0] = *(const f32x4*)(cw + k * 512 + c0); w[k][1] = *(const f32x4*)(cw + k * 512 + c0 + 4); }
;     for (int r = gw; r < MP; r += NGW) {
;         v4u* dst = (v4u*)(AO + (size_t)r * 1024 + 512 + c0);
;         if (r >= M_REAL) { *dst = (v4u){0u, 0u, 0u, 0u}; *(v4u*)(AO + (size_t)r * 1024 + c0) = (v4u){0u, 0u, 0u, 0u}; continue; }
; template <int LYR>
; __device__ __forceinline__ void layer_phases(const Args& a, const XcdBarrier& bar, unsigned char* lds, int lo, int hi) {
;     ...
;         { LAUNDER_BASES(); conv_pass(P_GB, P_U, a.in[9] + (size_t)LYR * 3 * 512, P_AO, gw, NGW, lane); }
;         __syncthreads();
.LBB0_506:
	v_mov_b32_e32 v255, 2
	s_cmp_lt_i32 s94, 4
	s_cselect_b64 s[2:3], -1, 0
	v_writelane_b32 v250, s2, 20
	s_and_b64 s[0:1], s[2:3], s[0:1]
	s_andn2_b64 vcc, exec, s[0:1]
	v_writelane_b32 v250, s3, 21
	v_writelane_b32 v250, s96, 22
	s_nop 1
	v_writelane_b32 v250, s97, 23
	v_writelane_b32 v250, s71, 24
	v_writelane_b32 v250, s88, 25
	s_nop 1
	v_writelane_b32 v250, s89, 26
	v_writelane_b32 v250, s90, 27
	v_writelane_b32 v250, s91, 28
	v_writelane_b32 v250, s92, 29
	v_writelane_b32 v250, s93, 30
	v_writelane_b32 v250, s94, 31
	v_writelane_b32 v250, s95, 32
	s_cbranch_vccnz .LBB0_612
	v_mov_b32_e32 v255, 0
	s_mov_b32 s20, 0x6000
	s_mov_b32 s21, 0
	s_mov_b32 s22, s96
	s_branch .Lconv_common_l0
.Lconv_do_l0:
	s_mov_b32 s20, 0x10200
	s_mov_b32 s21, 0x5c40
	s_movk_i32 s22, 136
.Lconv_common_l0:
	s_mov_b64 s[2:3], s[92:93]
	s_mov_b64 s[0:1], s[90:91]
	v_mov_b32_e32 v0, v182
	v_readfirstlane_b32 s0, v183
	s_lshr_b32 s1, s0, 6
	s_mov_b32 s4, s70
	s_mov_b32 s0, s96
	s_lshl_b32 s4, s4, 3
	s_add_i32 s4, s4, s21
	s_mov_b32 s0, s22
	s_add_i32 s1, s4, s1
	s_cmp_ge_i32 s1, s20
	s_cbranch_scc1 .LBB0_522
	v_lshlrev_b32_e32 v24, 3, v0
	v_readlane_b32 s4, v250, 2
	s_waitcnt lgkmcnt(0)
	v_ashrrev_i32_e32 v25, 31, v24
	v_readlane_b32 s6, v250, 4
	v_readlane_b32 s7, v250, 5
	v_readlane_b32 s5, v250, 3
	s_mov_b64 s[4:5], 0x1000
	v_lshl_add_u64 v[20:21], v[24:25], 2, s[6:7]
	v_add_co_u32_e32 v16, vcc, 0x1000, v20
	global_load_dwordx4 v[0:3], v[20:21], off offset:2048
	global_load_dwordx4 v[4:7], v[20:21], off
	global_load_dwordx4 v[8:11], v[20:21], off offset:2064
	global_load_dwordx4 v[12:15], v[20:21], off offset:16
	v_addc_co_u32_e32 v17, vcc, 0, v21, vcc
	v_lshl_add_u64 v[20:21], v[20:21], 0, s[4:5]
	global_load_dwordx4 v[16:19], v[16:17], off
	v_readlane_b32 s10, v250, 8
	global_load_dwordx4 v[20:23], v[20:21], off offset:16
	v_readlane_b32 s11, v250, 9
	v_readlane_b32 s12, v250, 10
	v_readlane_b32 s13, v250, 11
	v_readlane_b32 s8, v250, 6
	v_readlane_b32 s9, v250, 7
	s_mov_b64 s[4:5], 0xc100000
	s_mov_b64 s[10:11], 0x10180000
	s_mov_b64 s[12:13], 0x14200000
	v_lshl_add_u64 v[24:25], v[24:25], 1, s[2:3]
	s_lshl_b32 s6, s0, 3
	s_mov_b32 s0, 0
	s_add_i32 s7, s1, 0xffff3ef0
	s_mov_b32 s8, 0xffff0000
	s_movk_i32 s9, 0x7fff
	v_lshl_add_u64 v[38:39], v[24:25], 0, s[4:5]
	v_lshl_add_u64 v[40:41], v[24:25], 0, s[10:11]
	v_lshl_add_u64 v[42:43], v[24:25], 0, s[12:13]
	v_mov_b32_e32 v48, 0x4010
	v_readlane_b32 s14, v250, 12
	v_readlane_b32 s15, v250, 13
	v_readlane_b32 s16, v250, 14
	v_readlane_b32 s17, v250, 15
	v_readlane_b32 s18, v250, 16
	v_readlane_b32 s19, v250, 17
	s_waitcnt vmcnt(5)
	v_mov_b32_e32 v44, v1
	v_mov_b32_e32 v45, v3
	s_waitcnt vmcnt(4)
	v_mov_b32_e32 v46, v5
	v_mov_b32_e32 v47, v7
	v_mov_b32_e32 v1, v2
	v_mov_b32_e32 v5, v6
	s_waitcnt vmcnt(3)
	v_mov_b32_e32 v2, v9
	v_mov_b32_e32 v3, v11
	s_waitcnt vmcnt(2)
	v_mov_b32_e32 v6, v13
	v_mov_b32_e32 v7, v15
	v_mov_b32_e32 v9, v10
	v_mov_b32_e32 v13, v14
	s_waitcnt vmcnt(1)
	v_mov_b32_e32 v10, v17
	v_mov_b32_e32 v11, v19
	v_mov_b32_e32 v17, v18
	s_waitcnt vmcnt(0)
	v_mov_b32_e32 v14, v21
	v_mov_b32_e32 v15, v23
	v_mov_b32_e32 v21, v22
	s_branch .LBB0_510
.LBB0_509:
	s_add_i32 s7, s7, s6
	s_add_i32 s1, s7, 0xc110
	s_cmp_lt_i32 s1, s20
	s_cbranch_scc0 .LBB0_522

; template <int LYR>
; __device__ __forceinline__ void layer_phases(const Args& a, const XcdBarrier& bar, unsigned char* lds, int lo, int hi) {
;     ...
;         { LAUNDER_BASES(); conv_pass(P_GB, P_U, a.in[9] + (size_t)LYR * 3 * 512, P_AO, gw, NGW, lane); }
;         __syncthreads();
;         { LAUNDER_BASES();
;           for (int i = 0;; ++i) {
;             constexpr bool LASTL = (LYR == NLAYER - 1);
;             const int id = LASTL ? attn_next_last(i, G, bx) : attn_next(i, G, bx); if (id < 0) break;
.LBB0_522:
	v_readfirstlane_b32 vcc_lo, v255
	s_cmp_lg_u32 vcc_lo, 0
	s_cbranch_scc1 .LBB0_612
	s_cmp_lt_u32 s70, 120
	s_cselect_b32 vcc_lo, 2, 1
	v_mov_b32_e32 v255, vcc_lo
